# pipelined attn_finish (counted vmcnt) + batched LDS bias reads in local-attention chunks
# speedup vs baseline: 1.0694x; 1.0032x over previous
.LBB0_615:
	v_and_b32_e32 v19, 64, v195
	v_readlane_b32 s0, v246, 36
	v_xor_b32_e32 v1, 32, v195
	v_add_u32_e32 v19, 64, v19
	v_lshlrev_b64 v[22:23], 1, v[114:115]
	v_readlane_b32 s1, v246, 37
	v_or_b32_e32 v18, s6, v18
	v_cmp_lt_i32_e32 vcc, v1, v19
	v_lshl_add_u64 v[20:21], s[0:1], 0, v[22:23]
	v_mul_i32_i24_e32 v18, 0x14000, v18
	v_mov_b32_e32 v19, v0
	v_lshl_add_u64 v[20:21], v[20:21], 0, v[18:19]
	s_mov_b32 s101, 0
	s_mov_b32 s100, 0x14000
	v_lshl_add_u64 v[250:251], v[20:21], 0, s[100:101]
	global_load_ushort v255, v[250:251], off
	s_mov_b32 s100, 0x28000
	v_lshl_add_u64 v[252:253], v[20:21], 0, s[100:101]
	global_load_ushort v255, v[252:253], off
	s_mov_b32 s100, 0x3c000
	v_lshl_add_u64 v[250:251], v[20:21], 0, s[100:101]
	global_load_ushort v255, v[250:251], off
	s_mov_b32 s100, 0xa0000
	v_lshl_add_u64 v[252:253], v[20:21], 0, s[100:101]
	global_load_ushort v255, v[252:253], off
	s_mov_b32 s100, 0xb4000
	v_lshl_add_u64 v[250:251], v[20:21], 0, s[100:101]
	global_load_ushort v255, v[250:251], off
	s_mov_b32 s100, 0xc8000
	v_lshl_add_u64 v[252:253], v[20:21], 0, s[100:101]
	global_load_ushort v255, v[252:253], off
	s_mov_b32 s100, 0xdc000
	v_lshl_add_u64 v[250:251], v[20:21], 0, s[100:101]
	global_load_ushort v255, v[250:251], off
	s_mov_b32 s100, 0x140000
	v_lshl_add_u64 v[252:253], v[20:21], 0, s[100:101]
	global_load_ushort v255, v[252:253], off
	s_mov_b32 s100, 0x154000
	v_lshl_add_u64 v[250:251], v[20:21], 0, s[100:101]
	global_load_ushort v255, v[250:251], off
	s_mov_b32 s100, 0x168000
	v_lshl_add_u64 v[252:253], v[20:21], 0, s[100:101]
	global_load_ushort v255, v[252:253], off
	s_mov_b32 s100, 0x17c000
	v_lshl_add_u64 v[250:251], v[20:21], 0, s[100:101]
	global_load_ushort v255, v[250:251], off
	s_mov_b32 s100, 0x1e0000
	v_lshl_add_u64 v[252:253], v[20:21], 0, s[100:101]
	global_load_ushort v255, v[252:253], off
	s_mov_b32 s100, 0x1f4000
	v_lshl_add_u64 v[250:251], v[20:21], 0, s[100:101]
	global_load_ushort v255, v[250:251], off
	s_mov_b32 s100, 0x208000
	v_lshl_add_u64 v[252:253], v[20:21], 0, s[100:101]
	global_load_ushort v255, v[252:253], off
	s_mov_b32 s100, 0x21c000
	v_lshl_add_u64 v[250:251], v[20:21], 0, s[100:101]
	global_load_ushort v255, v[250:251], off
	s_mov_b32 s100, 0x280000
	v_lshl_add_u64 v[252:253], v[20:21], 0, s[100:101]
	global_load_ushort v255, v[252:253], off
	s_mov_b32 s100, 0x294000
	v_lshl_add_u64 v[250:251], v[20:21], 0, s[100:101]
	global_load_ushort v255, v[250:251], off
	s_mov_b32 s100, 0x2a8000
	v_lshl_add_u64 v[252:253], v[20:21], 0, s[100:101]
	global_load_ushort v255, v[252:253], off
	s_mov_b32 s100, 0x2bc000
	v_lshl_add_u64 v[250:251], v[20:21], 0, s[100:101]
	global_load_ushort v255, v[250:251], off
	s_mov_b32 s100, 0x320000
	v_lshl_add_u64 v[252:253], v[20:21], 0, s[100:101]
	global_load_ushort v255, v[252:253], off
	s_mov_b32 s100, 0x334000
	v_lshl_add_u64 v[250:251], v[20:21], 0, s[100:101]
	global_load_ushort v255, v[250:251], off
	s_mov_b32 s100, 0x348000
	v_lshl_add_u64 v[252:253], v[20:21], 0, s[100:101]
	global_load_ushort v255, v[252:253], off
	s_mov_b32 s100, 0x35c000
	v_lshl_add_u64 v[250:251], v[20:21], 0, s[100:101]
	global_load_ushort v255, v[250:251], off
	s_mov_b32 s100, 0x3c0000
	v_lshl_add_u64 v[252:253], v[20:21], 0, s[100:101]
	global_load_ushort v255, v[252:253], off
	s_mov_b32 s100, 0x3d4000
	v_lshl_add_u64 v[250:251], v[20:21], 0, s[100:101]
	global_load_ushort v255, v[250:251], off
	s_mov_b32 s100, 0x3e8000
	v_lshl_add_u64 v[252:253], v[20:21], 0, s[100:101]
	global_load_ushort v255, v[252:253], off
	s_mov_b32 s100, 0x3fc000
	v_lshl_add_u64 v[250:251], v[20:21], 0, s[100:101]
	global_load_ushort v255, v[250:251], off
	s_mov_b32 s100, 0x460000
	v_lshl_add_u64 v[252:253], v[20:21], 0, s[100:101]
	global_load_ushort v255, v[252:253], off
	s_mov_b32 s100, 0x474000
	v_lshl_add_u64 v[250:251], v[20:21], 0, s[100:101]
	global_load_ushort v255, v[250:251], off
	s_mov_b32 s100, 0x488000
	v_lshl_add_u64 v[252:253], v[20:21], 0, s[100:101]
	global_load_ushort v255, v[252:253], off
	s_mov_b32 s100, 0x49c000
	v_lshl_add_u64 v[250:251], v[20:21], 0, s[100:101]
	global_load_ushort v255, v[250:251], off
	global_load_ushort v24, v[20:21], off
	v_cndmask_b32_e32 v1, v195, v1, vcc
	v_lshlrev_b32_e32 v1, 2, v1
	ds_bpermute_b32 v1, v1, v66
	v_lshl_add_u64 v[18:19], s[68:69], 0, v[18:19]
	v_lshl_add_u64 v[18:19], v[18:19], 0, v[22:23]
	s_movk_i32 s77, 0xc00
	s_waitcnt lgkmcnt(0)
	v_add_f32_e32 v1, v66, v1
	v_rcp_f32_e32 v1, v1
	s_nop 0
	s_mov_b32 s101, 0
	s_mov_b32 s100, 0x14000
	v_lshl_add_u64 v[250:251], v[20:21], 0, s[100:101]
	global_load_ushort v249, v[250:251], off
	s_waitcnt vmcnt(1)
	v_lshlrev_b32_e32 v24, 16, v24
	v_mul_f32_e32 v250, v50, v1
	v_mul_f32_e32 v250, v250, v24
	v_cvt_pk_bf16_f32 v250, v250, v250
	s_mov_b32 s100, 0xd84a000
	v_lshl_add_u64 v[252:253], v[18:19], 0, s[100:101]
	global_store_short v[252:253], v250, off
	s_mov_b32 s100, 0x28000
	v_lshl_add_u64 v[250:251], v[20:21], 0, s[100:101]
	global_load_ushort v254, v[250:251], off
	s_waitcnt vmcnt(2)
	v_lshlrev_b32_e32 v249, 16, v249
	v_mul_f32_e32 v250, v51, v1
	v_mul_f32_e32 v250, v250, v249
	v_cvt_pk_bf16_f32 v250, v250, v250
	s_mov_b32 s100, 0xd85e000
	v_lshl_add_u64 v[252:253], v[18:19], 0, s[100:101]
	global_store_short v[252:253], v250, off
	s_mov_b32 s100, 0x3c000
	v_lshl_add_u64 v[250:251], v[20:21], 0, s[100:101]
	global_load_ushort v255, v[250:251], off
	s_waitcnt vmcnt(2)
	v_lshlrev_b32_e32 v254, 16, v254
	v_mul_f32_e32 v250, v52, v1
	v_mul_f32_e32 v250, v250, v254
	v_cvt_pk_bf16_f32 v250, v250, v250
	s_mov_b32 s100, 0xd872000
	v_lshl_add_u64 v[252:253], v[18:19], 0, s[100:101]
	global_store_short v[252:253], v250, off
	s_mov_b32 s100, 0xa0000
	v_lshl_add_u64 v[250:251], v[20:21], 0, s[100:101]
	global_load_ushort v249, v[250:251], off
	s_waitcnt vmcnt(2)
	v_lshlrev_b32_e32 v255, 16, v255
	v_mul_f32_e32 v250, v53, v1
	v_mul_f32_e32 v250, v250, v255
	v_cvt_pk_bf16_f32 v250, v250, v250
	s_mov_b32 s100, 0xd886000
	v_lshl_add_u64 v[252:253], v[18:19], 0, s[100:101]
	global_store_short v[252:253], v250, off
	s_mov_b32 s100, 0xb4000
	v_lshl_add_u64 v[250:251], v[20:21], 0, s[100:101]
	global_load_ushort v254, v[250:251], off
	s_waitcnt vmcnt(2)
	v_lshlrev_b32_e32 v249, 16, v249
	v_mul_f32_e32 v250, v54, v1
	v_mul_f32_e32 v250, v250, v249
	v_cvt_pk_bf16_f32 v250, v250, v250
	s_mov_b32 s100, 0xd8ea000
	v_lshl_add_u64 v[252:253], v[18:19], 0, s[100:101]
	global_store_short v[252:253], v250, off
	s_mov_b32 s100, 0xc8000
	v_lshl_add_u64 v[250:251], v[20:21], 0, s[100:101]
	global_load_ushort v255, v[250:251], off
	s_waitcnt vmcnt(2)
	v_lshlrev_b32_e32 v254, 16, v254
	v_mul_f32_e32 v250, v55, v1
	v_mul_f32_e32 v250, v250, v254
	v_cvt_pk_bf16_f32 v250, v250, v250
	s_mov_b32 s100, 0xd8fe000
	v_lshl_add_u64 v[252:253], v[18:19], 0, s[100:101]
	global_store_short v[252:253], v250, off
	s_mov_b32 s100, 0xdc000
	v_lshl_add_u64 v[250:251], v[20:21], 0, s[100:101]
	global_load_ushort v249, v[250:251], off
	s_waitcnt vmcnt(2)
	v_lshlrev_b32_e32 v255, 16, v255
	v_mul_f32_e32 v250, v56, v1
	v_mul_f32_e32 v250, v250, v255
	v_cvt_pk_bf16_f32 v250, v250, v250
	s_mov_b32 s100, 0xd912000
	v_lshl_add_u64 v[252:253], v[18:19], 0, s[100:101]
	global_store_short v[252:253], v250, off
	s_mov_b32 s100, 0x140000
	v_lshl_add_u64 v[250:251], v[20:21], 0, s[100:101]
	global_load_ushort v254, v[250:251], off
	s_waitcnt vmcnt(2)
	v_lshlrev_b32_e32 v249, 16, v249
	v_mul_f32_e32 v250, v57, v1
	v_mul_f32_e32 v250, v250, v249
	v_cvt_pk_bf16_f32 v250, v250, v250
	s_mov_b32 s100, 0xd926000
	v_lshl_add_u64 v[252:253], v[18:19], 0, s[100:101]
	global_store_short v[252:253], v250, off
	s_mov_b32 s100, 0x154000
	v_lshl_add_u64 v[250:251], v[20:21], 0, s[100:101]
	global_load_ushort v255, v[250:251], off
	s_waitcnt vmcnt(2)
	v_lshlrev_b32_e32 v254, 16, v254
	v_mul_f32_e32 v250, v58, v1
	v_mul_f32_e32 v250, v250, v254
	v_cvt_pk_bf16_f32 v250, v250, v250
	s_mov_b32 s100, 0xd98a000
	v_lshl_add_u64 v[252:253], v[18:19], 0, s[100:101]
	global_store_short v[252:253], v250, off
	s_mov_b32 s100, 0x168000
	v_lshl_add_u64 v[250:251], v[20:21], 0, s[100:101]
	global_load_ushort v249, v[250:251], off
	s_waitcnt vmcnt(2)
	v_lshlrev_b32_e32 v255, 16, v255
	v_mul_f32_e32 v250, v59, v1
	v_mul_f32_e32 v250, v250, v255
	v_cvt_pk_bf16_f32 v250, v250, v250
	s_mov_b32 s100, 0xd99e000
	v_lshl_add_u64 v[252:253], v[18:19], 0, s[100:101]
	global_store_short v[252:253], v250, off
	s_mov_b32 s100, 0x17c000
	v_lshl_add_u64 v[250:251], v[20:21], 0, s[100:101]
	global_load_ushort v254, v[250:251], off
	s_waitcnt vmcnt(2)
	v_lshlrev_b32_e32 v249, 16, v249
	v_mul_f32_e32 v250, v60, v1
	v_mul_f32_e32 v250, v250, v249
	v_cvt_pk_bf16_f32 v250, v250, v250
	s_mov_b32 s100, 0xd9b2000
	v_lshl_add_u64 v[252:253], v[18:19], 0, s[100:101]
	global_store_short v[252:253], v250, off
	s_mov_b32 s100, 0x1e0000
	v_lshl_add_u64 v[250:251], v[20:21], 0, s[100:101]
	global_load_ushort v255, v[250:251], off
	s_waitcnt vmcnt(2)
	v_lshlrev_b32_e32 v254, 16, v254
	v_mul_f32_e32 v250, v61, v1
	v_mul_f32_e32 v250, v250, v254
	v_cvt_pk_bf16_f32 v250, v250, v250
	s_mov_b32 s100, 0xd9c6000
	v_lshl_add_u64 v[252:253], v[18:19], 0, s[100:101]
	global_store_short v[252:253], v250, off
	s_mov_b32 s100, 0x1f4000
	v_lshl_add_u64 v[250:251], v[20:21], 0, s[100:101]
	global_load_ushort v249, v[250:251], off
	s_waitcnt vmcnt(2)
	v_lshlrev_b32_e32 v255, 16, v255
	v_mul_f32_e32 v250, v62, v1
	v_mul_f32_e32 v250, v250, v255
	v_cvt_pk_bf16_f32 v250, v250, v250
	s_mov_b32 s100, 0xda2a000
	v_lshl_add_u64 v[252:253], v[18:19], 0, s[100:101]
	global_store_short v[252:253], v250, off
	s_mov_b32 s100, 0x208000
	v_lshl_add_u64 v[250:251], v[20:21], 0, s[100:101]
	global_load_ushort v254, v[250:251], off
	s_waitcnt vmcnt(2)
	v_lshlrev_b32_e32 v249, 16, v249
	v_mul_f32_e32 v250, v63, v1
	v_mul_f32_e32 v250, v250, v249
	v_cvt_pk_bf16_f32 v250, v250, v250
	s_mov_b32 s100, 0xda3e000
	v_lshl_add_u64 v[252:253], v[18:19], 0, s[100:101]
	global_store_short v[252:253], v250, off
	s_mov_b32 s100, 0x21c000
	v_lshl_add_u64 v[250:251], v[20:21], 0, s[100:101]
	global_load_ushort v255, v[250:251], off
	s_waitcnt vmcnt(2)
	v_lshlrev_b32_e32 v254, 16, v254
	v_mul_f32_e32 v250, v64, v1
	v_mul_f32_e32 v250, v250, v254
	v_cvt_pk_bf16_f32 v250, v250, v250
	s_mov_b32 s100, 0xda52000
	v_lshl_add_u64 v[252:253], v[18:19], 0, s[100:101]
	global_store_short v[252:253], v250, off
	s_mov_b32 s100, 0x280000
	v_lshl_add_u64 v[250:251], v[20:21], 0, s[100:101]
	global_load_ushort v249, v[250:251], off
	s_waitcnt vmcnt(2)
	v_lshlrev_b32_e32 v255, 16, v255
	v_mul_f32_e32 v250, v65, v1
	v_mul_f32_e32 v250, v250, v255
	v_cvt_pk_bf16_f32 v250, v250, v250
	s_mov_b32 s100, 0xda66000
	v_lshl_add_u64 v[252:253], v[18:19], 0, s[100:101]
	global_store_short v[252:253], v250, off
	s_mov_b32 s100, 0x294000
	v_lshl_add_u64 v[250:251], v[20:21], 0, s[100:101]
	global_load_ushort v254, v[250:251], off
	s_waitcnt vmcnt(2)
	v_lshlrev_b32_e32 v249, 16, v249
	v_mul_f32_e32 v250, v2, v1
	v_mul_f32_e32 v250, v250, v249
	v_cvt_pk_bf16_f32 v250, v250, v250
	s_mov_b32 s100, 0xdaca000
	v_lshl_add_u64 v[252:253], v[18:19], 0, s[100:101]
	global_store_short v[252:253], v250, off
	s_mov_b32 s100, 0x2a8000
	v_lshl_add_u64 v[250:251], v[20:21], 0, s[100:101]
	global_load_ushort v255, v[250:251], off
	s_waitcnt vmcnt(2)
	v_lshlrev_b32_e32 v254, 16, v254
	v_mul_f32_e32 v250, v3, v1
	v_mul_f32_e32 v250, v250, v254
	v_cvt_pk_bf16_f32 v250, v250, v250
	s_mov_b32 s100, 0xdade000
	v_lshl_add_u64 v[252:253], v[18:19], 0, s[100:101]
	global_store_short v[252:253], v250, off
	s_mov_b32 s100, 0x2bc000
	v_lshl_add_u64 v[250:251], v[20:21], 0, s[100:101]
	global_load_ushort v249, v[250:251], off
	s_waitcnt vmcnt(2)
	v_lshlrev_b32_e32 v255, 16, v255
	v_mul_f32_e32 v250, v4, v1
	v_mul_f32_e32 v250, v250, v255
	v_cvt_pk_bf16_f32 v250, v250, v250
	s_mov_b32 s100, 0xdaf2000
	v_lshl_add_u64 v[252:253], v[18:19], 0, s[100:101]
	global_store_short v[252:253], v250, off
	s_mov_b32 s100, 0x320000
	v_lshl_add_u64 v[250:251], v[20:21], 0, s[100:101]
	global_load_ushort v254, v[250:251], off
	s_waitcnt vmcnt(2)
	v_lshlrev_b32_e32 v249, 16, v249
	v_mul_f32_e32 v250, v5, v1
	v_mul_f32_e32 v250, v250, v249
	v_cvt_pk_bf16_f32 v250, v250, v250
	s_mov_b32 s100, 0xdb06000
	v_lshl_add_u64 v[252:253], v[18:19], 0, s[100:101]
	global_store_short v[252:253], v250, off
	s_mov_b32 s100, 0x334000
	v_lshl_add_u64 v[250:251], v[20:21], 0, s[100:101]
	global_load_ushort v255, v[250:251], off
	s_waitcnt vmcnt(2)
	v_lshlrev_b32_e32 v254, 16, v254
	v_mul_f32_e32 v250, v6, v1
	v_mul_f32_e32 v250, v250, v254
	v_cvt_pk_bf16_f32 v250, v250, v250
	s_mov_b32 s100, 0xdb6a000
	v_lshl_add_u64 v[252:253], v[18:19], 0, s[100:101]
	global_store_short v[252:253], v250, off
	s_mov_b32 s100, 0x348000
	v_lshl_add_u64 v[250:251], v[20:21], 0, s[100:101]
	global_load_ushort v249, v[250:251], off
	s_waitcnt vmcnt(2)
	v_lshlrev_b32_e32 v255, 16, v255
	v_mul_f32_e32 v250, v7, v1
	v_mul_f32_e32 v250, v250, v255
	v_cvt_pk_bf16_f32 v250, v250, v250
	s_mov_b32 s100, 0xdb7e000
	v_lshl_add_u64 v[252:253], v[18:19], 0, s[100:101]
	global_store_short v[252:253], v250, off
	s_mov_b32 s100, 0x35c000
	v_lshl_add_u64 v[250:251], v[20:21], 0, s[100:101]
	global_load_ushort v254, v[250:251], off
	s_waitcnt vmcnt(2)
	v_lshlrev_b32_e32 v249, 16, v249
	v_mul_f32_e32 v250, v8, v1
	v_mul_f32_e32 v250, v250, v249
	v_cvt_pk_bf16_f32 v250, v250, v250
	s_mov_b32 s100, 0xdb92000
	v_lshl_add_u64 v[252:253], v[18:19], 0, s[100:101]
	global_store_short v[252:253], v250, off
	s_mov_b32 s100, 0x3c0000
	v_lshl_add_u64 v[250:251], v[20:21], 0, s[100:101]
	global_load_ushort v255, v[250:251], off
	s_waitcnt vmcnt(2)
	v_lshlrev_b32_e32 v254, 16, v254
	v_mul_f32_e32 v250, v9, v1
	v_mul_f32_e32 v250, v250, v254
	v_cvt_pk_bf16_f32 v250, v250, v250
	s_mov_b32 s100, 0xdba6000
	v_lshl_add_u64 v[252:253], v[18:19], 0, s[100:101]
	global_store_short v[252:253], v250, off
	s_mov_b32 s100, 0x3d4000
	v_lshl_add_u64 v[250:251], v[20:21], 0, s[100:101]
	global_load_ushort v249, v[250:251], off
	s_waitcnt vmcnt(2)
	v_lshlrev_b32_e32 v255, 16, v255
	v_mul_f32_e32 v250, v10, v1
	v_mul_f32_e32 v250, v250, v255
	v_cvt_pk_bf16_f32 v250, v250, v250
	s_mov_b32 s100, 0xdc0a000
	v_lshl_add_u64 v[252:253], v[18:19], 0, s[100:101]
	global_store_short v[252:253], v250, off
	s_mov_b32 s100, 0x3e8000
	v_lshl_add_u64 v[250:251], v[20:21], 0, s[100:101]
	global_load_ushort v254, v[250:251], off
	s_waitcnt vmcnt(2)
	v_lshlrev_b32_e32 v249, 16, v249
	v_mul_f32_e32 v250, v11, v1
	v_mul_f32_e32 v250, v250, v249
	v_cvt_pk_bf16_f32 v250, v250, v250
	s_mov_b32 s100, 0xdc1e000
	v_lshl_add_u64 v[252:253], v[18:19], 0, s[100:101]
	global_store_short v[252:253], v250, off
	s_mov_b32 s100, 0x3fc000
	v_lshl_add_u64 v[250:251], v[20:21], 0, s[100:101]
	global_load_ushort v255, v[250:251], off
	s_waitcnt vmcnt(2)
	v_lshlrev_b32_e32 v254, 16, v254
	v_mul_f32_e32 v250, v12, v1
	v_mul_f32_e32 v250, v250, v254
	v_cvt_pk_bf16_f32 v250, v250, v250
	s_mov_b32 s100, 0xdc32000
	v_lshl_add_u64 v[252:253], v[18:19], 0, s[100:101]
	global_store_short v[252:253], v250, off
	s_mov_b32 s100, 0x460000
	v_lshl_add_u64 v[250:251], v[20:21], 0, s[100:101]
	global_load_ushort v249, v[250:251], off
	s_waitcnt vmcnt(2)
	v_lshlrev_b32_e32 v255, 16, v255
	v_mul_f32_e32 v250, v13, v1
	v_mul_f32_e32 v250, v250, v255
	v_cvt_pk_bf16_f32 v250, v250, v250
	s_mov_b32 s100, 0xdc46000
	v_lshl_add_u64 v[252:253], v[18:19], 0, s[100:101]
	global_store_short v[252:253], v250, off
	s_mov_b32 s100, 0x474000
	v_lshl_add_u64 v[250:251], v[20:21], 0, s[100:101]
	global_load_ushort v254, v[250:251], off
	s_waitcnt vmcnt(2)
	v_lshlrev_b32_e32 v249, 16, v249
	v_mul_f32_e32 v250, v14, v1
	v_mul_f32_e32 v250, v250, v249
	v_cvt_pk_bf16_f32 v250, v250, v250
	s_mov_b32 s100, 0xdcaa000
	v_lshl_add_u64 v[252:253], v[18:19], 0, s[100:101]
	global_store_short v[252:253], v250, off
	s_mov_b32 s100, 0x488000
	v_lshl_add_u64 v[250:251], v[20:21], 0, s[100:101]
	global_load_ushort v255, v[250:251], off
	s_waitcnt vmcnt(2)
	v_lshlrev_b32_e32 v254, 16, v254
	v_mul_f32_e32 v250, v15, v1
	v_mul_f32_e32 v250, v250, v254
	v_cvt_pk_bf16_f32 v250, v250, v250
	s_mov_b32 s100, 0xdcbe000
	v_lshl_add_u64 v[252:253], v[18:19], 0, s[100:101]
	global_store_short v[252:253], v250, off
	s_mov_b32 s100, 0x49c000
	v_lshl_add_u64 v[250:251], v[20:21], 0, s[100:101]
	global_load_ushort v249, v[250:251], off
	s_waitcnt vmcnt(2)
	v_lshlrev_b32_e32 v255, 16, v255
	v_mul_f32_e32 v250, v16, v1
	v_mul_f32_e32 v250, v250, v255
	v_cvt_pk_bf16_f32 v250, v250, v250
	s_mov_b32 s100, 0xdcd2000
	v_lshl_add_u64 v[252:253], v[18:19], 0, s[100:101]
	global_store_short v[252:253], v250, off
	s_waitcnt vmcnt(1)
	v_lshlrev_b32_e32 v249, 16, v249
	v_mul_f32_e32 v250, v17, v1
	v_mul_f32_e32 v250, v250, v249
	v_cvt_pk_bf16_f32 v250, v250, v250
	s_mov_b32 s100, 0xdce6000
	v_lshl_add_u64 v[252:253], v[18:19], 0, s[100:101]
	global_store_short v[252:253], v250, off

.LBB0_704:
	v_readlane_b32 s0, v246, 36
	v_lshlrev_b64 v[34:35], 1, v[82:83]
	v_readlane_b32 s1, v246, 37
	v_lshl_or_b32 v38, v98, 2, s2
	v_mul_u32_u24_e32 v38, 0x14000, v38
	v_lshl_add_u64 v[36:37], s[0:1], 0, v[34:35]
	v_mov_b32_e32 v39, v0
	v_lshl_add_u64 v[36:37], v[36:37], 0, v[38:39]
	s_mov_b32 s101, 0
	s_mov_b32 s100, 0x14000
	v_lshl_add_u64 v[250:251], v[36:37], 0, s[100:101]
	global_load_ushort v255, v[250:251], off
	s_mov_b32 s100, 0x28000
	v_lshl_add_u64 v[252:253], v[36:37], 0, s[100:101]
	global_load_ushort v255, v[252:253], off
	s_mov_b32 s100, 0x3c000
	v_lshl_add_u64 v[250:251], v[36:37], 0, s[100:101]
	global_load_ushort v255, v[250:251], off
	s_mov_b32 s100, 0xa0000
	v_lshl_add_u64 v[252:253], v[36:37], 0, s[100:101]
	global_load_ushort v255, v[252:253], off
	s_mov_b32 s100, 0xb4000
	v_lshl_add_u64 v[250:251], v[36:37], 0, s[100:101]
	global_load_ushort v255, v[250:251], off
	s_mov_b32 s100, 0xc8000
	v_lshl_add_u64 v[252:253], v[36:37], 0, s[100:101]
	global_load_ushort v255, v[252:253], off
	s_mov_b32 s100, 0xdc000
	v_lshl_add_u64 v[250:251], v[36:37], 0, s[100:101]
	global_load_ushort v255, v[250:251], off
	s_mov_b32 s100, 0x140000
	v_lshl_add_u64 v[252:253], v[36:37], 0, s[100:101]
	global_load_ushort v255, v[252:253], off
	s_mov_b32 s100, 0x154000
	v_lshl_add_u64 v[250:251], v[36:37], 0, s[100:101]
	global_load_ushort v255, v[250:251], off
	s_mov_b32 s100, 0x168000
	v_lshl_add_u64 v[252:253], v[36:37], 0, s[100:101]
	global_load_ushort v255, v[252:253], off
	s_mov_b32 s100, 0x17c000
	v_lshl_add_u64 v[250:251], v[36:37], 0, s[100:101]
	global_load_ushort v255, v[250:251], off
	s_mov_b32 s100, 0x1e0000
	v_lshl_add_u64 v[252:253], v[36:37], 0, s[100:101]
	global_load_ushort v255, v[252:253], off
	s_mov_b32 s100, 0x1f4000
	v_lshl_add_u64 v[250:251], v[36:37], 0, s[100:101]
	global_load_ushort v255, v[250:251], off
	s_mov_b32 s100, 0x208000
	v_lshl_add_u64 v[252:253], v[36:37], 0, s[100:101]
	global_load_ushort v255, v[252:253], off
	s_mov_b32 s100, 0x21c000
	v_lshl_add_u64 v[250:251], v[36:37], 0, s[100:101]
	global_load_ushort v255, v[250:251], off
	s_mov_b32 s100, 0x280000
	v_lshl_add_u64 v[252:253], v[36:37], 0, s[100:101]
	global_load_ushort v255, v[252:253], off
	s_mov_b32 s100, 0x294000
	v_lshl_add_u64 v[250:251], v[36:37], 0, s[100:101]
	global_load_ushort v255, v[250:251], off
	s_mov_b32 s100, 0x2a8000
	v_lshl_add_u64 v[252:253], v[36:37], 0, s[100:101]
	global_load_ushort v255, v[252:253], off
	s_mov_b32 s100, 0x2bc000
	v_lshl_add_u64 v[250:251], v[36:37], 0, s[100:101]
	global_load_ushort v255, v[250:251], off
	s_mov_b32 s100, 0x320000
	v_lshl_add_u64 v[252:253], v[36:37], 0, s[100:101]
	global_load_ushort v255, v[252:253], off
	s_mov_b32 s100, 0x334000
	v_lshl_add_u64 v[250:251], v[36:37], 0, s[100:101]
	global_load_ushort v255, v[250:251], off
	s_mov_b32 s100, 0x348000
	v_lshl_add_u64 v[252:253], v[36:37], 0, s[100:101]
	global_load_ushort v255, v[252:253], off
	s_mov_b32 s100, 0x35c000
	v_lshl_add_u64 v[250:251], v[36:37], 0, s[100:101]
	global_load_ushort v255, v[250:251], off
	s_mov_b32 s100, 0x3c0000
	v_lshl_add_u64 v[252:253], v[36:37], 0, s[100:101]
	global_load_ushort v255, v[252:253], off
	s_mov_b32 s100, 0x3d4000
	v_lshl_add_u64 v[250:251], v[36:37], 0, s[100:101]
	global_load_ushort v255, v[250:251], off
	s_mov_b32 s100, 0x3e8000
	v_lshl_add_u64 v[252:253], v[36:37], 0, s[100:101]
	global_load_ushort v255, v[252:253], off
	s_mov_b32 s100, 0x3fc000
	v_lshl_add_u64 v[250:251], v[36:37], 0, s[100:101]
	global_load_ushort v255, v[250:251], off
	s_mov_b32 s100, 0x460000
	v_lshl_add_u64 v[252:253], v[36:37], 0, s[100:101]
	global_load_ushort v255, v[252:253], off
	s_mov_b32 s100, 0x474000
	v_lshl_add_u64 v[250:251], v[36:37], 0, s[100:101]
	global_load_ushort v255, v[250:251], off
	s_mov_b32 s100, 0x488000
	v_lshl_add_u64 v[252:253], v[36:37], 0, s[100:101]
	global_load_ushort v255, v[252:253], off
	s_mov_b32 s100, 0x49c000
	v_lshl_add_u64 v[250:251], v[36:37], 0, s[100:101]
	global_load_ushort v255, v[250:251], off
	global_load_ushort v40, v[36:37], off
	ds_bpermute_b32 v1, v87, v103
	v_lshl_add_u64 v[38:39], s[68:69], 0, v[38:39]
	v_lshl_add_u64 v[34:35], v[38:39], 0, v[34:35]
	s_waitcnt lgkmcnt(0)
	v_add_f32_e32 v1, v103, v1
	v_rcp_f32_e32 v1, v1
	s_nop 0
	s_mov_b32 s101, 0
	s_mov_b32 s100, 0x14000
	v_lshl_add_u64 v[250:251], v[36:37], 0, s[100:101]
	global_load_ushort v249, v[250:251], off
	s_waitcnt vmcnt(1)
	v_lshlrev_b32_e32 v40, 16, v40
	v_mul_f32_e32 v250, v18, v1
	v_mul_f32_e32 v250, v250, v40
	v_cvt_pk_bf16_f32 v250, v250, v250
	s_mov_b32 s100, 0xd84a000
	v_lshl_add_u64 v[252:253], v[34:35], 0, s[100:101]
	global_store_short v[252:253], v250, off
	s_mov_b32 s100, 0x28000
	v_lshl_add_u64 v[250:251], v[36:37], 0, s[100:101]
	global_load_ushort v254, v[250:251], off
	s_waitcnt vmcnt(2)
	v_lshlrev_b32_e32 v249, 16, v249
	v_mul_f32_e32 v250, v19, v1
	v_mul_f32_e32 v250, v250, v249
	v_cvt_pk_bf16_f32 v250, v250, v250
	s_mov_b32 s100, 0xd85e000
	v_lshl_add_u64 v[252:253], v[34:35], 0, s[100:101]
	global_store_short v[252:253], v250, off
	s_mov_b32 s100, 0x3c000
	v_lshl_add_u64 v[250:251], v[36:37], 0, s[100:101]
	global_load_ushort v255, v[250:251], off
	s_waitcnt vmcnt(2)
	v_lshlrev_b32_e32 v254, 16, v254
	v_mul_f32_e32 v250, v20, v1
	v_mul_f32_e32 v250, v250, v254
	v_cvt_pk_bf16_f32 v250, v250, v250
	s_mov_b32 s100, 0xd872000
	v_lshl_add_u64 v[252:253], v[34:35], 0, s[100:101]
	global_store_short v[252:253], v250, off
	s_mov_b32 s100, 0xa0000
	v_lshl_add_u64 v[250:251], v[36:37], 0, s[100:101]
	global_load_ushort v249, v[250:251], off
	s_waitcnt vmcnt(2)
	v_lshlrev_b32_e32 v255, 16, v255
	v_mul_f32_e32 v250, v21, v1
	v_mul_f32_e32 v250, v250, v255
	v_cvt_pk_bf16_f32 v250, v250, v250
	s_mov_b32 s100, 0xd886000
	v_lshl_add_u64 v[252:253], v[34:35], 0, s[100:101]
	global_store_short v[252:253], v250, off
	s_mov_b32 s100, 0xb4000
	v_lshl_add_u64 v[250:251], v[36:37], 0, s[100:101]
	global_load_ushort v254, v[250:251], off
	s_waitcnt vmcnt(2)
	v_lshlrev_b32_e32 v249, 16, v249
	v_mul_f32_e32 v250, v22, v1
	v_mul_f32_e32 v250, v250, v249
	v_cvt_pk_bf16_f32 v250, v250, v250
	s_mov_b32 s100, 0xd8ea000
	v_lshl_add_u64 v[252:253], v[34:35], 0, s[100:101]
	global_store_short v[252:253], v250, off
	s_mov_b32 s100, 0xc8000
	v_lshl_add_u64 v[250:251], v[36:37], 0, s[100:101]
	global_load_ushort v255, v[250:251], off
	s_waitcnt vmcnt(2)
	v_lshlrev_b32_e32 v254, 16, v254
	v_mul_f32_e32 v250, v23, v1
	v_mul_f32_e32 v250, v250, v254
	v_cvt_pk_bf16_f32 v250, v250, v250
	s_mov_b32 s100, 0xd8fe000
	v_lshl_add_u64 v[252:253], v[34:35], 0, s[100:101]
	global_store_short v[252:253], v250, off
	s_mov_b32 s100, 0xdc000
	v_lshl_add_u64 v[250:251], v[36:37], 0, s[100:101]
	global_load_ushort v249, v[250:251], off
	s_waitcnt vmcnt(2)
	v_lshlrev_b32_e32 v255, 16, v255
	v_mul_f32_e32 v250, v24, v1
	v_mul_f32_e32 v250, v250, v255
	v_cvt_pk_bf16_f32 v250, v250, v250
	s_mov_b32 s100, 0xd912000
	v_lshl_add_u64 v[252:253], v[34:35], 0, s[100:101]
	global_store_short v[252:253], v250, off
	s_mov_b32 s100, 0x140000
	v_lshl_add_u64 v[250:251], v[36:37], 0, s[100:101]
	global_load_ushort v254, v[250:251], off
	s_waitcnt vmcnt(2)
	v_lshlrev_b32_e32 v249, 16, v249
	v_mul_f32_e32 v250, v25, v1
	v_mul_f32_e32 v250, v250, v249
	v_cvt_pk_bf16_f32 v250, v250, v250
	s_mov_b32 s100, 0xd926000
	v_lshl_add_u64 v[252:253], v[34:35], 0, s[100:101]
	global_store_short v[252:253], v250, off
	s_mov_b32 s100, 0x154000
	v_lshl_add_u64 v[250:251], v[36:37], 0, s[100:101]
	global_load_ushort v255, v[250:251], off
	s_waitcnt vmcnt(2)
	v_lshlrev_b32_e32 v254, 16, v254
	v_mul_f32_e32 v250, v26, v1
	v_mul_f32_e32 v250, v250, v254
	v_cvt_pk_bf16_f32 v250, v250, v250
	s_mov_b32 s100, 0xd98a000
	v_lshl_add_u64 v[252:253], v[34:35], 0, s[100:101]
	global_store_short v[252:253], v250, off
	s_mov_b32 s100, 0x168000
	v_lshl_add_u64 v[250:251], v[36:37], 0, s[100:101]
	global_load_ushort v249, v[250:251], off
	s_waitcnt vmcnt(2)
	v_lshlrev_b32_e32 v255, 16, v255
	v_mul_f32_e32 v250, v27, v1
	v_mul_f32_e32 v250, v250, v255
	v_cvt_pk_bf16_f32 v250, v250, v250
	s_mov_b32 s100, 0xd99e000
	v_lshl_add_u64 v[252:253], v[34:35], 0, s[100:101]
	global_store_short v[252:253], v250, off
	s_mov_b32 s100, 0x17c000
	v_lshl_add_u64 v[250:251], v[36:37], 0, s[100:101]
	global_load_ushort v254, v[250:251], off
	s_waitcnt vmcnt(2)
	v_lshlrev_b32_e32 v249, 16, v249
	v_mul_f32_e32 v250, v28, v1
	v_mul_f32_e32 v250, v250, v249
	v_cvt_pk_bf16_f32 v250, v250, v250
	s_mov_b32 s100, 0xd9b2000
	v_lshl_add_u64 v[252:253], v[34:35], 0, s[100:101]
	global_store_short v[252:253], v250, off
	s_mov_b32 s100, 0x1e0000
	v_lshl_add_u64 v[250:251], v[36:37], 0, s[100:101]
	global_load_ushort v255, v[250:251], off
	s_waitcnt vmcnt(2)
	v_lshlrev_b32_e32 v254, 16, v254
	v_mul_f32_e32 v250, v29, v1
	v_mul_f32_e32 v250, v250, v254
	v_cvt_pk_bf16_f32 v250, v250, v250
	s_mov_b32 s100, 0xd9c6000
	v_lshl_add_u64 v[252:253], v[34:35], 0, s[100:101]
	global_store_short v[252:253], v250, off
	s_mov_b32 s100, 0x1f4000
	v_lshl_add_u64 v[250:251], v[36:37], 0, s[100:101]
	global_load_ushort v249, v[250:251], off
	s_waitcnt vmcnt(2)
	v_lshlrev_b32_e32 v255, 16, v255
	v_mul_f32_e32 v250, v30, v1
	v_mul_f32_e32 v250, v250, v255
	v_cvt_pk_bf16_f32 v250, v250, v250
	s_mov_b32 s100, 0xda2a000
	v_lshl_add_u64 v[252:253], v[34:35], 0, s[100:101]
	global_store_short v[252:253], v250, off
	s_mov_b32 s100, 0x208000
	v_lshl_add_u64 v[250:251], v[36:37], 0, s[100:101]
	global_load_ushort v254, v[250:251], off
	s_waitcnt vmcnt(2)
	v_lshlrev_b32_e32 v249, 16, v249
	v_mul_f32_e32 v250, v31, v1
	v_mul_f32_e32 v250, v250, v249
	v_cvt_pk_bf16_f32 v250, v250, v250
	s_mov_b32 s100, 0xda3e000
	v_lshl_add_u64 v[252:253], v[34:35], 0, s[100:101]
	global_store_short v[252:253], v250, off
	s_mov_b32 s100, 0x21c000
	v_lshl_add_u64 v[250:251], v[36:37], 0, s[100:101]
	global_load_ushort v255, v[250:251], off
	s_waitcnt vmcnt(2)
	v_lshlrev_b32_e32 v254, 16, v254
	v_mul_f32_e32 v250, v32, v1
	v_mul_f32_e32 v250, v250, v254
	v_cvt_pk_bf16_f32 v250, v250, v250
	s_mov_b32 s100, 0xda52000
	v_lshl_add_u64 v[252:253], v[34:35], 0, s[100:101]
	global_store_short v[252:253], v250, off
	s_mov_b32 s100, 0x280000
	v_lshl_add_u64 v[250:251], v[36:37], 0, s[100:101]
	global_load_ushort v249, v[250:251], off
	s_waitcnt vmcnt(2)
	v_lshlrev_b32_e32 v255, 16, v255
	v_mul_f32_e32 v250, v33, v1
	v_mul_f32_e32 v250, v250, v255
	v_cvt_pk_bf16_f32 v250, v250, v250
	s_mov_b32 s100, 0xda66000
	v_lshl_add_u64 v[252:253], v[34:35], 0, s[100:101]
	global_store_short v[252:253], v250, off
	s_mov_b32 s100, 0x294000
	v_lshl_add_u64 v[250:251], v[36:37], 0, s[100:101]
	global_load_ushort v254, v[250:251], off
	s_waitcnt vmcnt(2)
	v_lshlrev_b32_e32 v249, 16, v249
	v_mul_f32_e32 v250, v2, v1
	v_mul_f32_e32 v250, v250, v249
	v_cvt_pk_bf16_f32 v250, v250, v250
	s_mov_b32 s100, 0xdaca000
	v_lshl_add_u64 v[252:253], v[34:35], 0, s[100:101]
	global_store_short v[252:253], v250, off
	s_mov_b32 s100, 0x2a8000
	v_lshl_add_u64 v[250:251], v[36:37], 0, s[100:101]
	global_load_ushort v255, v[250:251], off
	s_waitcnt vmcnt(2)
	v_lshlrev_b32_e32 v254, 16, v254
	v_mul_f32_e32 v250, v3, v1
	v_mul_f32_e32 v250, v250, v254
	v_cvt_pk_bf16_f32 v250, v250, v250
	s_mov_b32 s100, 0xdade000
	v_lshl_add_u64 v[252:253], v[34:35], 0, s[100:101]
	global_store_short v[252:253], v250, off
	s_mov_b32 s100, 0x2bc000
	v_lshl_add_u64 v[250:251], v[36:37], 0, s[100:101]
	global_load_ushort v249, v[250:251], off
	s_waitcnt vmcnt(2)
	v_lshlrev_b32_e32 v255, 16, v255
	v_mul_f32_e32 v250, v4, v1
	v_mul_f32_e32 v250, v250, v255
	v_cvt_pk_bf16_f32 v250, v250, v250
	s_mov_b32 s100, 0xdaf2000
	v_lshl_add_u64 v[252:253], v[34:35], 0, s[100:101]
	global_store_short v[252:253], v250, off
	s_mov_b32 s100, 0x320000
	v_lshl_add_u64 v[250:251], v[36:37], 0, s[100:101]
	global_load_ushort v254, v[250:251], off
	s_waitcnt vmcnt(2)
	v_lshlrev_b32_e32 v249, 16, v249
	v_mul_f32_e32 v250, v5, v1
	v_mul_f32_e32 v250, v250, v249
	v_cvt_pk_bf16_f32 v250, v250, v250
	s_mov_b32 s100, 0xdb06000
	v_lshl_add_u64 v[252:253], v[34:35], 0, s[100:101]
	global_store_short v[252:253], v250, off
	s_mov_b32 s100, 0x334000
	v_lshl_add_u64 v[250:251], v[36:37], 0, s[100:101]
	global_load_ushort v255, v[250:251], off
	s_waitcnt vmcnt(2)
	v_lshlrev_b32_e32 v254, 16, v254
	v_mul_f32_e32 v250, v6, v1
	v_mul_f32_e32 v250, v250, v254
	v_cvt_pk_bf16_f32 v250, v250, v250
	s_mov_b32 s100, 0xdb6a000
	v_lshl_add_u64 v[252:253], v[34:35], 0, s[100:101]
	global_store_short v[252:253], v250, off
	s_mov_b32 s100, 0x348000
	v_lshl_add_u64 v[250:251], v[36:37], 0, s[100:101]
	global_load_ushort v249, v[250:251], off
	s_waitcnt vmcnt(2)
	v_lshlrev_b32_e32 v255, 16, v255
	v_mul_f32_e32 v250, v7, v1
	v_mul_f32_e32 v250, v250, v255
	v_cvt_pk_bf16_f32 v250, v250, v250
	s_mov_b32 s100, 0xdb7e000
	v_lshl_add_u64 v[252:253], v[34:35], 0, s[100:101]
	global_store_short v[252:253], v250, off
	s_mov_b32 s100, 0x35c000
	v_lshl_add_u64 v[250:251], v[36:37], 0, s[100:101]
	global_load_ushort v254, v[250:251], off
	s_waitcnt vmcnt(2)
	v_lshlrev_b32_e32 v249, 16, v249
	v_mul_f32_e32 v250, v8, v1
	v_mul_f32_e32 v250, v250, v249
	v_cvt_pk_bf16_f32 v250, v250, v250
	s_mov_b32 s100, 0xdb92000
	v_lshl_add_u64 v[252:253], v[34:35], 0, s[100:101]
	global_store_short v[252:253], v250, off
	s_mov_b32 s100, 0x3c0000
	v_lshl_add_u64 v[250:251], v[36:37], 0, s[100:101]
	global_load_ushort v255, v[250:251], off
	s_waitcnt vmcnt(2)
	v_lshlrev_b32_e32 v254, 16, v254
	v_mul_f32_e32 v250, v9, v1
	v_mul_f32_e32 v250, v250, v254
	v_cvt_pk_bf16_f32 v250, v250, v250
	s_mov_b32 s100, 0xdba6000
	v_lshl_add_u64 v[252:253], v[34:35], 0, s[100:101]
	global_store_short v[252:253], v250, off
	s_mov_b32 s100, 0x3d4000
	v_lshl_add_u64 v[250:251], v[36:37], 0, s[100:101]
	global_load_ushort v249, v[250:251], off
	s_waitcnt vmcnt(2)
	v_lshlrev_b32_e32 v255, 16, v255
	v_mul_f32_e32 v250, v10, v1
	v_mul_f32_e32 v250, v250, v255
	v_cvt_pk_bf16_f32 v250, v250, v250
	s_mov_b32 s100, 0xdc0a000
	v_lshl_add_u64 v[252:253], v[34:35], 0, s[100:101]
	global_store_short v[252:253], v250, off
	s_mov_b32 s100, 0x3e8000
	v_lshl_add_u64 v[250:251], v[36:37], 0, s[100:101]
	global_load_ushort v254, v[250:251], off
	s_waitcnt vmcnt(2)
	v_lshlrev_b32_e32 v249, 16, v249
	v_mul_f32_e32 v250, v11, v1
	v_mul_f32_e32 v250, v250, v249
	v_cvt_pk_bf16_f32 v250, v250, v250
	s_mov_b32 s100, 0xdc1e000
	v_lshl_add_u64 v[252:253], v[34:35], 0, s[100:101]
	global_store_short v[252:253], v250, off
	s_mov_b32 s100, 0x3fc000
	v_lshl_add_u64 v[250:251], v[36:37], 0, s[100:101]
	global_load_ushort v255, v[250:251], off
	s_waitcnt vmcnt(2)
	v_lshlrev_b32_e32 v254, 16, v254
	v_mul_f32_e32 v250, v12, v1
	v_mul_f32_e32 v250, v250, v254
	v_cvt_pk_bf16_f32 v250, v250, v250
	s_mov_b32 s100, 0xdc32000
	v_lshl_add_u64 v[252:253], v[34:35], 0, s[100:101]
	global_store_short v[252:253], v250, off
	s_mov_b32 s100, 0x460000
	v_lshl_add_u64 v[250:251], v[36:37], 0, s[100:101]
	global_load_ushort v249, v[250:251], off
	s_waitcnt vmcnt(2)
	v_lshlrev_b32_e32 v255, 16, v255
	v_mul_f32_e32 v250, v13, v1
	v_mul_f32_e32 v250, v250, v255
	v_cvt_pk_bf16_f32 v250, v250, v250
	s_mov_b32 s100, 0xdc46000
	v_lshl_add_u64 v[252:253], v[34:35], 0, s[100:101]
	global_store_short v[252:253], v250, off
	s_mov_b32 s100, 0x474000
	v_lshl_add_u64 v[250:251], v[36:37], 0, s[100:101]
	global_load_ushort v254, v[250:251], off
	s_waitcnt vmcnt(2)
	v_lshlrev_b32_e32 v249, 16, v249
	v_mul_f32_e32 v250, v14, v1
	v_mul_f32_e32 v250, v250, v249
	v_cvt_pk_bf16_f32 v250, v250, v250
	s_mov_b32 s100, 0xdcaa000
	v_lshl_add_u64 v[252:253], v[34:35], 0, s[100:101]
	global_store_short v[252:253], v250, off
	s_mov_b32 s100, 0x488000
	v_lshl_add_u64 v[250:251], v[36:37], 0, s[100:101]
	global_load_ushort v255, v[250:251], off
	s_waitcnt vmcnt(2)
	v_lshlrev_b32_e32 v254, 16, v254
	v_mul_f32_e32 v250, v15, v1
	v_mul_f32_e32 v250, v250, v254
	v_cvt_pk_bf16_f32 v250, v250, v250
	s_mov_b32 s100, 0xdcbe000
	v_lshl_add_u64 v[252:253], v[34:35], 0, s[100:101]
	global_store_short v[252:253], v250, off
	s_mov_b32 s100, 0x49c000
	v_lshl_add_u64 v[250:251], v[36:37], 0, s[100:101]
	global_load_ushort v249, v[250:251], off
	s_waitcnt vmcnt(2)
	v_lshlrev_b32_e32 v255, 16, v255
	v_mul_f32_e32 v250, v16, v1
	v_mul_f32_e32 v250, v250, v255
	v_cvt_pk_bf16_f32 v250, v250, v250
	s_mov_b32 s100, 0xdcd2000
	v_lshl_add_u64 v[252:253], v[34:35], 0, s[100:101]
	global_store_short v[252:253], v250, off
	s_waitcnt vmcnt(1)
	v_lshlrev_b32_e32 v249, 16, v249
	v_mul_f32_e32 v250, v17, v1
	v_mul_f32_e32 v250, v250, v249
	v_cvt_pk_bf16_f32 v250, v250, v250
	s_mov_b32 s100, 0xdce6000
	v_lshl_add_u64 v[252:253], v[34:35], 0, s[100:101]
	global_store_short v[252:253], v250, off

.LBB0_729:
	s_add_i32 s0, s70, s77
	s_add_i32 s0, s0, -8
	v_cmp_ge_i32_e32 vcc, s0, v142
	v_cmp_lt_i32_e64 s[0:1], s0, v143
	v_mov_b64_e32 v[64:65], v[32:33]
	v_mov_b64_e32 v[2:3], v[34:35]
	s_and_b64 vcc, vcc, s[0:1]
	v_mov_b64_e32 v[62:63], v[30:31]
	v_mov_b64_e32 v[60:61], v[28:29]
	v_mov_b64_e32 v[58:59], v[26:27]
	v_mov_b64_e32 v[56:57], v[24:25]
	v_mov_b64_e32 v[54:55], v[22:23]
	v_mov_b64_e32 v[52:53], v[20:21]
	v_mov_b64_e32 v[50:51], v[18:19]
	v_mov_b64_e32 v[4:5], v[36:37]
	v_mov_b64_e32 v[6:7], v[38:39]
	v_mov_b64_e32 v[8:9], v[40:41]
	v_mov_b64_e32 v[10:11], v[42:43]
	v_mov_b64_e32 v[12:13], v[44:45]
	v_mov_b64_e32 v[14:15], v[46:47]
	v_mov_b64_e32 v[16:17], v[48:49]
	v_mov_b32_e32 v1, v179
	v_mov_b32_e32 v66, v180
	s_and_saveexec_b64 s[0:1], vcc
	s_cbranch_execz .LBB0_799
	v_add_u32_e32 v1, s47, v144
	v_add_u32_e32 v183, v1, v116
	ds_read_b128 v[2:5], v183
	ds_read_b128 v[50:53], v183 offset:32
	v_mov_b32_e32 v66, 0xff800000
	v_mov_b32_e32 v67, 0xff800000
	s_waitcnt vmcnt(3) lgkmcnt(1)
	v_mfma_f32_32x32x16_bf16 v[2:17], v[2:5], v[82:85], 0
	s_waitcnt vmcnt(2) lgkmcnt(0)
	v_mfma_f32_32x32x16_bf16 v[2:17], v[50:53], v[86:89], v[2:17]
	ds_read_b128 v[50:53], v183 offset:64
	s_waitcnt vmcnt(1) lgkmcnt(0)
	v_mfma_f32_32x32x16_bf16 v[2:17], v[50:53], v[90:93], v[2:17]
	ds_read_b128 v[50:53], v183 offset:96
	s_waitcnt vmcnt(0) lgkmcnt(0)
	v_mfma_f32_32x32x16_bf16 v[2:17], v[50:53], v[94:97], v[2:17]
	v_add_u32_e32 v249, v146, v145
	ds_read_b32 v249, v249 offset:36800
	v_add_u32_e32 v250, v146, v147
	ds_read_b32 v250, v250 offset:36800
	v_add_u32_e32 v251, v146, v148
	ds_read_b32 v251, v251 offset:36800
	v_add_u32_e32 v252, v146, v149
	ds_read_b32 v252, v252 offset:36800
	v_add_u32_e32 v253, v146, v150
	ds_read_b32 v253, v253 offset:36800
	v_add_u32_e32 v254, v146, v151
	ds_read_b32 v254, v254 offset:36800
	v_add_u32_e32 v255, v146, v152
	ds_read_b32 v255, v255 offset:36800
	s_waitcnt lgkmcnt(0)
	v_add_f32_e32 v249, v2, v249
	v_cndmask_b32_e64 v67, v67, v249, s[8:9]
	v_add_f32_e32 v250, v3, v250
	v_cndmask_b32_e64 v66, v66, v250, s[10:11]
	v_mov_b32_e32 v68, 0xff800000
	v_mov_b32_e32 v69, 0xff800000
	v_add_f32_e32 v251, v4, v251
	v_cndmask_b32_e64 v69, v69, v251, s[14:15]
	v_add_f32_e32 v252, v5, v252
	v_cndmask_b32_e64 v68, v68, v252, s[16:17]
	v_mov_b32_e32 v70, 0xff800000
	v_mov_b32_e32 v71, 0xff800000
	v_add_f32_e32 v253, v6, v253
	v_cndmask_b32_e64 v71, v71, v253, s[18:19]
	v_readlane_b32 s4, v244, 11
	v_readlane_b32 s5, v244, 12
	v_add_f32_e32 v254, v7, v254
	s_nop 0
	v_cndmask_b32_e64 v70, v70, v254, s[4:5]
	v_mov_b32_e32 v72, 0xff800000
	v_mov_b32_e32 v73, 0xff800000
	v_readlane_b32 s4, v244, 13
	v_readlane_b32 s5, v244, 14
	v_add_f32_e32 v255, v8, v255
	s_nop 0
	v_cndmask_b32_e64 v73, v73, v255, s[4:5]
	v_add_u32_e32 v249, v146, v153
	ds_read_b32 v249, v249 offset:36800
	v_add_u32_e32 v250, v146, v154
	ds_read_b32 v250, v250 offset:36740
	v_add_u32_e32 v251, v146, v155
	ds_read_b32 v251, v251 offset:36740
	v_add_u32_e32 v252, v146, v156
	ds_read_b32 v252, v252 offset:36740
	v_add_u32_e32 v253, v146, v157
	ds_read_b32 v253, v253 offset:36740
	v_add_u32_e32 v254, v146, v158
	ds_read_b32 v254, v254 offset:36740
	v_add_u32_e32 v255, v146, v159
	ds_read_b32 v255, v255 offset:36740
	s_waitcnt lgkmcnt(0)
	v_readlane_b32 s4, v244, 15
	v_readlane_b32 s5, v244, 16
	v_add_f32_e32 v249, v9, v249
	s_nop 0
	v_cndmask_b32_e64 v72, v72, v249, s[4:5]
	v_mov_b32_e32 v74, 0xff800000
	v_mov_b32_e32 v75, 0xff800000
	v_readlane_b32 s4, v244, 17
	v_readlane_b32 s5, v244, 18
	v_add_f32_e32 v250, v10, v250
	s_nop 0
	v_cndmask_b32_e64 v75, v75, v250, s[4:5]
	v_readlane_b32 s4, v244, 19
	v_readlane_b32 s5, v244, 20
	v_add_f32_e32 v251, v11, v251
	s_nop 0
	v_cndmask_b32_e64 v74, v74, v251, s[4:5]
	v_mov_b32_e32 v76, 0xff800000
	v_mov_b32_e32 v78, 0xff800000
	v_add_f32_e32 v252, v12, v252
	v_cndmask_b32_e64 v78, v78, v252, s[34:35]
	v_add_f32_e32 v253, v13, v253
	v_cndmask_b32_e64 v76, v76, v253, s[68:69]
	v_mov_b32_e32 v77, 0xff800000
	v_mov_b32_e32 v79, 0xff800000
	v_add_f32_e32 v254, v14, v254
	v_cndmask_b32_e64 v79, v79, v254, s[82:83]
	v_add_f32_e32 v255, v15, v255
	v_cndmask_b32_e64 v77, v77, v255, s[50:51]
	v_mov_b32_e32 v80, 0xff800000
	v_mov_b32_e32 v81, 0xff800000
	v_add_u32_e32 v249, v146, v160
	ds_read_b32 v249, v249 offset:36740
	v_add_u32_e32 v250, v146, v161
	ds_read_b32 v250, v250 offset:36740
	s_waitcnt lgkmcnt(0)
	v_add_f32_e32 v249, v16, v249
	v_cndmask_b32_e64 v81, v81, v249, s[88:89]
	v_add_f32_e32 v250, v17, v250
	v_cndmask_b32_e64 v80, v80, v250, s[90:91]
	v_and_b32_e32 v2, 64, v195
	v_xor_b32_e32 v1, 32, v195
	v_add_u32_e32 v2, 64, v2
	v_cmp_lt_i32_e32 vcc, v1, v2
	v_max_f32_e32 v2, v67, v67
	s_mov_b32 s4, 0x41000000
	v_cndmask_b32_e32 v1, v195, v1, vcc
	v_lshlrev_b32_e32 v202, 2, v1
	v_max_f32_e32 v1, v66, v66
	v_max_f32_e32 v1, v2, v1
	v_max3_f32 v1, v1, v69, v68
	v_max3_f32 v1, v1, v71, v70
	v_max3_f32 v1, v1, v73, v72
	v_max3_f32 v1, v1, v75, v74
	v_max3_f32 v1, v1, v78, v76
	v_max3_f32 v1, v1, v79, v77
	v_max3_f32 v1, v1, v81, v80
	ds_bpermute_b32 v2, v202, v1
	v_mov_b64_e32 v[64:65], v[32:33]
	v_mov_b32_e32 v203, v180
	v_mov_b64_e32 v[62:63], v[30:31]
	v_mov_b64_e32 v[60:61], v[28:29]
	s_waitcnt lgkmcnt(0)
	v_max_f32_e32 v2, v2, v2
	v_max_f32_e32 v181, v1, v2
	v_sub_f32_e32 v1, v181, v179
	v_mov_b64_e32 v[2:3], v[34:35]
	v_cmp_lt_f32_e32 vcc, s4, v1
	v_mov_b32_e32 v1, v179
	v_mov_b64_e32 v[4:5], v[36:37]
	v_mov_b64_e32 v[6:7], v[38:39]
	v_mov_b64_e32 v[8:9], v[40:41]
	v_mov_b64_e32 v[10:11], v[42:43]
	v_mov_b64_e32 v[12:13], v[44:45]
	v_mov_b64_e32 v[14:15], v[46:47]
	v_mov_b64_e32 v[16:17], v[48:49]
	v_mov_b64_e32 v[58:59], v[26:27]
	v_mov_b64_e32 v[56:57], v[24:25]
	v_mov_b64_e32 v[54:55], v[22:23]
	v_mov_b64_e32 v[52:53], v[20:21]
	v_mov_b64_e32 v[50:51], v[18:19]
	s_cbranch_vccz .LBB0_764
	v_max_f32_e32 v1, v181, v181
	v_max_f32_e32 v2, v179, v179
	v_max_f32_e32 v1, v2, v1
	v_sub_f32_e32 v2, v179, v1
	v_exp_f32_e32 v2, v2
	s_nop 0
	v_mul_f32_e32 v203, v180, v2
	v_pk_mul_f32 v[64:65], v[32:33], v[2:3] op_sel_hi:[1,0]
	v_pk_mul_f32 v[62:63], v[30:31], v[2:3] op_sel_hi:[1,0]
	v_pk_mul_f32 v[60:61], v[28:29], v[2:3] op_sel_hi:[1,0]
	v_pk_mul_f32 v[58:59], v[26:27], v[2:3] op_sel_hi:[1,0]
	v_pk_mul_f32 v[56:57], v[24:25], v[2:3] op_sel_hi:[1,0]
	v_pk_mul_f32 v[54:55], v[22:23], v[2:3] op_sel_hi:[1,0]
	v_pk_mul_f32 v[52:53], v[20:21], v[2:3] op_sel_hi:[1,0]
	v_pk_mul_f32 v[50:51], v[18:19], v[2:3] op_sel_hi:[1,0]
	v_pk_mul_f32 v[16:17], v[48:49], v[2:3] op_sel_hi:[1,0]
	v_pk_mul_f32 v[14:15], v[46:47], v[2:3] op_sel_hi:[1,0]
	v_pk_mul_f32 v[12:13], v[44:45], v[2:3] op_sel_hi:[1,0]
	v_pk_mul_f32 v[10:11], v[42:43], v[2:3] op_sel_hi:[1,0]
	v_pk_mul_f32 v[8:9], v[40:41], v[2:3] op_sel_hi:[1,0]
	v_pk_mul_f32 v[6:7], v[38:39], v[2:3] op_sel_hi:[1,0]
	v_pk_mul_f32 v[4:5], v[36:37], v[2:3] op_sel_hi:[1,0]
	v_pk_mul_f32 v[2:3], v[34:35], v[2:3] op_sel_hi:[1,0]
.LBB0_764:
	v_sub_f32_e32 v66, v66, v1
	v_exp_f32_e32 v206, v66
	v_sub_f32_e32 v66, v69, v1
	v_exp_f32_e32 v207, v66
	v_sub_f32_e32 v66, v68, v1
	v_exp_f32_e32 v208, v66
	v_sub_f32_e32 v66, v71, v1
	v_exp_f32_e32 v209, v66
	v_sub_f32_e32 v66, v70, v1
	v_exp_f32_e32 v210, v66
	v_sub_f32_e32 v66, v73, v1
	v_exp_f32_e32 v211, v66
	v_sub_f32_e32 v66, v72, v1
	v_exp_f32_e32 v212, v66
	v_sub_f32_e32 v66, v75, v1
	v_exp_f32_e32 v213, v66
	v_sub_f32_e32 v66, v78, v1
	v_exp_f32_e32 v214, v66
	v_add_u32_e32 v66, s47, v141
	v_add_u32_e32 v75, v66, v144
	v_sub_f32_e32 v67, v67, v1
	v_add_u32_e32 v182, 0x2000, v75
	v_exp_f32_e32 v205, v67
	ds_read2_b64 v[66:69], v182 offset0:128 offset1:130
	v_add_u32_e32 v181, 0x3000, v75
	ds_read2_b64 v[220:223], v181 offset0:192 offset1:194
	v_cvt_pk_bf16_f32 v73, v211, v212
	v_cvt_pk_bf16_f32 v72, v209, v210
	v_cvt_pk_bf16_f32 v71, v207, v208
	v_cvt_pk_bf16_f32 v70, v205, v206
	v_sub_f32_e32 v74, v74, v1
	v_sub_f32_e32 v76, v76, v1
	s_waitcnt lgkmcnt(1)
	v_mfma_f32_32x32x16_bf16 v[50:65], v[66:69], v[70:73], v[50:65]
	v_sub_f32_e32 v66, v81, v1
	v_exp_f32_e32 v215, v66
	v_sub_f32_e32 v66, v80, v1
	v_exp_f32_e32 v216, v66
	ds_read2_b64 v[66:69], v182 offset0:132 offset1:134
	v_sub_f32_e32 v78, v79, v1
	v_sub_f32_e32 v75, v77, v1
	v_exp_f32_e32 v218, v78
	s_waitcnt lgkmcnt(1)
	v_mfma_f32_32x32x16_bf16 v[2:17], v[220:223], v[70:73], v[2:17]
	v_exp_f32_e32 v217, v75
	v_exp_f32_e32 v219, v76
	v_exp_f32_e32 v220, v74
	v_cvt_pk_bf16_f32 v73, v215, v216
	v_cvt_pk_bf16_f32 v72, v218, v217
	v_cvt_pk_bf16_f32 v71, v214, v219
	v_cvt_pk_bf16_f32 v70, v213, v220
	ds_read_b128 v[222:225], v183 offset:4640
	v_mov_b32_e32 v204, 0xff800000
	s_waitcnt lgkmcnt(1)
	v_mfma_f32_32x32x16_bf16 v[50:65], v[66:69], v[70:73], v[50:65]
	ds_read2_b64 v[66:69], v181 offset0:196 offset1:198
	s_waitcnt lgkmcnt(0)
	v_mfma_f32_32x32x16_bf16 v[2:17], v[66:69], v[70:73], v[2:17]
	ds_read_b128 v[66:69], v183 offset:4608
	s_waitcnt lgkmcnt(0)
	v_mfma_f32_32x32x16_bf16 v[66:81], v[66:69], v[82:85], 0
	v_mfma_f32_32x32x16_bf16 v[66:81], v[222:225], v[86:89], v[66:81]
	ds_read_b128 v[222:225], v183 offset:4672
	s_waitcnt lgkmcnt(0)
	v_mfma_f32_32x32x16_bf16 v[66:81], v[222:225], v[90:93], v[66:81]
	ds_read_b128 v[222:225], v183 offset:4704
	v_mov_b32_e32 v183, 0xff800000
	s_waitcnt lgkmcnt(0)
	v_mfma_f32_32x32x16_bf16 v[66:81], v[222:225], v[94:97], v[66:81]
	v_add_u32_e32 v249, v146, v162
	ds_read_b32 v249, v249 offset:36740
	v_add_u32_e32 v250, v146, v163
	ds_read_b32 v250, v250 offset:36740
	v_add_u32_e32 v251, v146, v164
	ds_read_b32 v251, v251 offset:36740
	v_add_u32_e32 v252, v146, v165
	ds_read_b32 v252, v252 offset:36740
	v_add_u32_e32 v253, v146, v166
	ds_read_b32 v253, v253 offset:36740
	v_add_u32_e32 v254, v146, v167
	ds_read_b32 v254, v254 offset:36740
	v_add_u32_e32 v255, v146, v168
	ds_read_b32 v255, v255 offset:36740
	s_waitcnt lgkmcnt(0)
	v_add_f32_e32 v249, v66, v249
	v_cndmask_b32_e64 v204, v204, v249, s[92:93]
	v_add_f32_e32 v250, v67, v250
	v_cndmask_b32_e64 v183, v183, v250, s[94:95]
	v_mov_b32_e32 v66, 0xff800000
	v_mov_b32_e32 v67, 0xff800000
	v_add_f32_e32 v251, v68, v251
	v_cndmask_b32_e64 v67, v67, v251, s[96:97]
	v_add_f32_e32 v252, v69, v252
	v_cndmask_b32_e64 v66, v66, v252, s[36:37]
	v_mov_b32_e32 v68, 0xff800000
	v_mov_b32_e32 v69, 0xff800000
	v_add_f32_e32 v253, v70, v253
	v_cndmask_b32_e64 v69, v69, v253, s[38:39]
	v_add_f32_e32 v254, v71, v254
	v_cndmask_b32_e64 v68, v68, v254, s[40:41]
	v_mov_b32_e32 v70, 0xff800000
	v_mov_b32_e32 v71, 0xff800000
	v_add_f32_e32 v255, v72, v255
	v_cndmask_b32_e64 v71, v71, v255, s[42:43]
	v_add_u32_e32 v249, v146, v169
	ds_read_b32 v249, v249 offset:36740
	v_add_u32_e32 v250, v146, v170
	ds_read_b32 v250, v250 offset:36740
	v_add_u32_e32 v251, v146, v171
	ds_read_b32 v251, v251 offset:36740
	v_add_u32_e32 v252, v146, v172
	ds_read_b32 v252, v252 offset:36740
	v_add_u32_e32 v253, v146, v173
	ds_read_b32 v253, v253 offset:36740
	v_add_u32_e32 v254, v146, v174
	ds_read_b32 v254, v254 offset:36740
	v_add_u32_e32 v255, v146, v175
	ds_read_b32 v255, v255 offset:36740
	s_waitcnt lgkmcnt(0)
	v_add_f32_e32 v249, v73, v249
	v_cndmask_b32_e64 v70, v70, v249, s[44:45]
	v_mov_b32_e32 v73, 0xff800000
	v_mov_b32_e32 v221, 0xff800000
	v_add_f32_e32 v250, v74, v250
	v_cndmask_b32_e64 v221, v221, v250, s[52:53]
	v_add_f32_e32 v251, v75, v251
	v_cndmask_b32_e64 v73, v73, v251, s[54:55]
	v_mov_b32_e32 v72, 0xff800000
	v_mov_b32_e32 v75, 0xff800000
	v_add_f32_e32 v252, v76, v252
	v_cndmask_b32_e64 v75, v75, v252, s[56:57]
	v_add_f32_e32 v253, v77, v253
	v_cndmask_b32_e64 v72, v72, v253, s[58:59]
	v_mov_b32_e32 v74, 0xff800000
	v_mov_b32_e32 v76, 0xff800000
	v_add_f32_e32 v254, v78, v254
	v_cndmask_b32_e64 v76, v76, v254, s[60:61]
	v_add_f32_e32 v255, v79, v255
	v_cndmask_b32_e64 v74, v74, v255, s[62:63]
	v_mov_b32_e32 v77, 0xff800000
	v_mov_b32_e32 v78, 0xff800000
	v_add_u32_e32 v249, v146, v176
	ds_read_b32 v249, v249 offset:36740
	v_add_u32_e32 v250, v146, v177
	ds_read_b32 v250, v250 offset:36740
	s_waitcnt lgkmcnt(0)
	v_add_f32_e32 v249, v80, v249
	v_cndmask_b32_e64 v78, v78, v249, s[64:65]
	v_add_f32_e32 v250, v81, v250
	v_cndmask_b32_e64 v77, v77, v250, s[66:67]
	v_max_f32_e32 v80, v183, v183
	v_max_f32_e32 v81, v204, v204
	v_add_f32_e32 v79, 0, v205
	v_max_f32_e32 v80, v81, v80
	v_add_f32_e32 v79, v206, v79
	v_max3_f32 v80, v80, v67, v66
	v_add_f32_e32 v79, v207, v79
	v_max3_f32 v80, v80, v69, v68
	v_add_f32_e32 v79, v208, v79
	v_max3_f32 v80, v80, v71, v70
	v_add_f32_e32 v79, v209, v79
	v_max3_f32 v80, v80, v221, v73
	v_add_f32_e32 v79, v210, v79
	v_max3_f32 v80, v80, v75, v72
	v_add_f32_e32 v79, v211, v79
	v_max3_f32 v80, v80, v76, v74
	v_add_f32_e32 v79, v212, v79
	v_max3_f32 v80, v80, v78, v77
	v_add_f32_e32 v79, v213, v79
	ds_bpermute_b32 v81, v202, v80
	v_add_f32_e32 v79, v220, v79
	v_add_f32_e32 v79, v214, v79
	v_add_f32_e32 v79, v219, v79
	v_add_f32_e32 v79, v218, v79
	v_add_f32_e32 v79, v217, v79
	s_waitcnt lgkmcnt(0)
	v_max_f32_e32 v81, v81, v81
	v_add_f32_e32 v79, v215, v79
	v_max_f32_e32 v80, v80, v81
	v_add_f32_e32 v79, v216, v79
	v_sub_f32_e32 v81, v80, v1
	v_add_f32_e32 v79, v203, v79
	v_cmp_lt_f32_e32 vcc, s4, v81
	s_cbranch_vccz .LBB0_798
	v_max_f32_e32 v80, v80, v80
	v_max_f32_e32 v81, v1, v1
	v_max_f32_e32 v81, v81, v80
	v_sub_f32_e32 v1, v1, v81
	v_exp_f32_e32 v80, v1
	v_mov_b32_e32 v1, v81
	v_mul_f32_e32 v79, v79, v80
	v_pk_mul_f32 v[64:65], v[64:65], v[80:81] op_sel_hi:[1,0]
	v_pk_mul_f32 v[62:63], v[62:63], v[80:81] op_sel_hi:[1,0]
	v_pk_mul_f32 v[60:61], v[60:61], v[80:81] op_sel_hi:[1,0]
	v_pk_mul_f32 v[58:59], v[58:59], v[80:81] op_sel_hi:[1,0]
	v_pk_mul_f32 v[56:57], v[56:57], v[80:81] op_sel_hi:[1,0]
	v_pk_mul_f32 v[54:55], v[54:55], v[80:81] op_sel_hi:[1,0]
	v_pk_mul_f32 v[52:53], v[52:53], v[80:81] op_sel_hi:[1,0]
	v_pk_mul_f32 v[50:51], v[50:51], v[80:81] op_sel_hi:[1,0]
	v_pk_mul_f32 v[16:17], v[16:17], v[80:81] op_sel_hi:[1,0]
	v_pk_mul_f32 v[14:15], v[14:15], v[80:81] op_sel_hi:[1,0]
	v_pk_mul_f32 v[12:13], v[12:13], v[80:81] op_sel_hi:[1,0]
	v_pk_mul_f32 v[10:11], v[10:11], v[80:81] op_sel_hi:[1,0]
	v_pk_mul_f32 v[8:9], v[8:9], v[80:81] op_sel_hi:[1,0]
	v_pk_mul_f32 v[6:7], v[6:7], v[80:81] op_sel_hi:[1,0]
	v_pk_mul_f32 v[4:5], v[4:5], v[80:81] op_sel_hi:[1,0]
	v_pk_mul_f32 v[2:3], v[2:3], v[80:81] op_sel_hi:[1,0]
